# adds: 12 layer-1 weight-transpose items per wave moved into the idle half-round of the layer-0 up-GEMM (blocks 128-255)
# speedup vs baseline: 1.0211x; 1.0007x over previous
.LBB0_130:
	s_or_b64 exec, exec, s[0:1]
	s_load_dwordx2 s[0:1], s[92:93], 0x58
	s_load_dwordx2 s[2:3], s[92:93], 0xb8
	s_load_dwordx2 s[4:5], s[92:93], 0xc0
	s_load_dwordx2 s[6:7], s[92:93], 0xc8
	s_load_dwordx2 s[8:9], s[92:93], 0xd0
	s_load_dwordx2 s[10:11], s[92:93], 0xe8
	v_and_b32_e32 v74, 63, v154
	v_lshrrev_b32_e32 v75, 6, v154
	v_mul_u32_u24_e32 v75, 0x2100, v75
	v_lshrrev_b32_e32 v3, 5, v74
	v_and_b32_e32 v4, 31, v74
	v_lshlrev_b32_e32 v4, 2, v4
	v_lshrrev_b32_e32 v5, 3, v74
	v_and_b32_e32 v6, 7, v74
	v_mul_u32_u24_e32 v2, 264, v6
	v_add_u32_e32 v2, v2, v5
	v_lshl_add_u32 v2, v2, 2, v75
	v_lshlrev_b32_e32 v6, 4, v6
	v_mul_u32_u24_e32 v1, 132, v5
	v_add3_u32 v1, v1, v6, v75
	v_readfirstlane_b32 s13, v154
	s_lshr_b32 s13, s13, 6
	s_lshl_b32 s26, s96, 3
	s_add_u32 s13, s13, s26
	s_mov_b32 s12, s13
	s_waitcnt lgkmcnt(0)
	s_cmp_ge_u32 s12, 54272
	s_cbranch_scc1 .Ltra_done
	s_cmp_ge_u32 s12, 33280
	s_cselect_b32 s41, 1, 0
	s_cselect_b32 s26, 33280, 0
	s_sub_u32 s42, s12, s26
	s_cmp_ge_u32 s42, 12288
	s_cbranch_scc1 .Ltra_m2
	s_mul_i32 s43, s42, 43691
	s_lshr_b32 s43, s43, 24
	s_mul_i32 s26, s43, 384
	s_sub_u32 s44, s42, s26
	s_mov_b32 s14, s0
	s_mov_b32 s15, s1
	s_mov_b32 s36, 0xc000
	s_mov_b32 s37, 0x6000000
	s_mov_b32 s38, 0x0
	s_mov_b32 s39, 0x3000000
	s_mov_b32 s40, 0x1000
	s_branch .Ltra_dec_done1

.Ltra_loop:
	s_add_u32 s12, s12, 2048
	s_cmp_lt_u32 s12, 54272
	s_cselect_b32 s24, 1, 0
	s_cbranch_scc0 .Ltra_nonext8
	s_cmp_ge_u32 s12, 33280
	s_cselect_b32 s41, 1, 0
	s_cselect_b32 s26, 33280, 0
	s_sub_u32 s42, s12, s26
	s_cmp_ge_u32 s42, 12288
	s_cbranch_scc1 .Ltra_m11
	s_mul_i32 s43, s42, 43691
	s_lshr_b32 s43, s43, 24
	s_mul_i32 s26, s43, 384
	s_sub_u32 s44, s42, s26
	s_mov_b32 s16, s0
	s_mov_b32 s17, s1
	s_mov_b32 s36, 0xc000
	s_mov_b32 s37, 0x6000000
	s_mov_b32 s38, 0x0
	s_mov_b32 s39, 0x3000000
	s_mov_b32 s40, 0x1000
	s_branch .Ltra_dec_done10

.Ltra_after9:
	ds_write_b32 v1, v10 offset:0
	ds_write_b32 v1, v11 offset:4
	ds_write_b32 v1, v12 offset:8
	ds_write_b32 v1, v13 offset:12
	ds_write_b32 v1, v14 offset:1056
	ds_write_b32 v1, v15 offset:1060
	ds_write_b32 v1, v16 offset:1064
	ds_write_b32 v1, v17 offset:1068
	ds_write_b32 v1, v18 offset:2112
	ds_write_b32 v1, v19 offset:2116
	ds_write_b32 v1, v20 offset:2120
	ds_write_b32 v1, v21 offset:2124
	ds_write_b32 v1, v22 offset:3168
	ds_write_b32 v1, v23 offset:3172
	ds_write_b32 v1, v24 offset:3176
	ds_write_b32 v1, v25 offset:3180
	ds_write_b32 v1, v26 offset:4224
	ds_write_b32 v1, v27 offset:4228
	ds_write_b32 v1, v28 offset:4232
	ds_write_b32 v1, v29 offset:4236
	ds_write_b32 v1, v30 offset:5280
	ds_write_b32 v1, v31 offset:5284
	ds_write_b32 v1, v32 offset:5288
	ds_write_b32 v1, v33 offset:5292
	ds_write_b32 v1, v34 offset:6336
	ds_write_b32 v1, v35 offset:6340
	ds_write_b32 v1, v36 offset:6344
	ds_write_b32 v1, v37 offset:6348
	ds_write_b32 v1, v38 offset:7392
	ds_write_b32 v1, v39 offset:7396
	ds_write_b32 v1, v40 offset:7400
	ds_write_b32 v1, v41 offset:7404
	v_mad_u32_u24 v9, v5, s22, v6
	s_lshl_b32 s46, s22, 3
	s_waitcnt lgkmcnt(0)
	ds_read_b32 v74, v2 offset:0
	ds_read_b32 v75, v2 offset:132
	ds_read_b32 v76, v2 offset:264
	ds_read_b32 v77, v2 offset:396
	ds_read_b32 v78, v2 offset:528
	ds_read_b32 v79, v2 offset:660
	ds_read_b32 v80, v2 offset:792
	ds_read_b32 v81, v2 offset:924
	ds_read_b32 v82, v2 offset:32
	ds_read_b32 v83, v2 offset:164
	ds_read_b32 v84, v2 offset:296
	ds_read_b32 v85, v2 offset:428
	ds_read_b32 v86, v2 offset:560
	ds_read_b32 v87, v2 offset:692
	ds_read_b32 v88, v2 offset:824
	ds_read_b32 v89, v2 offset:956
	s_waitcnt lgkmcnt(8)
	v_cvt_pk_bf16_f32 v106, v74, v75
	v_cvt_pk_bf16_f32 v107, v76, v77
	v_cvt_pk_bf16_f32 v108, v78, v79
	v_cvt_pk_bf16_f32 v109, v80, v81
	global_store_dwordx4 v9, v[106:109], s[18:19]
	s_add_u32 s18, s18, s46
	s_addc_u32 s19, s19, 0
	ds_read_b32 v90, v2 offset:64
	ds_read_b32 v91, v2 offset:196
	ds_read_b32 v92, v2 offset:328
	ds_read_b32 v93, v2 offset:460
	ds_read_b32 v94, v2 offset:592
	ds_read_b32 v95, v2 offset:724
	ds_read_b32 v96, v2 offset:856
	ds_read_b32 v97, v2 offset:988
	s_waitcnt lgkmcnt(8)
	v_cvt_pk_bf16_f32 v110, v82, v83
	v_cvt_pk_bf16_f32 v111, v84, v85
	v_cvt_pk_bf16_f32 v112, v86, v87
	v_cvt_pk_bf16_f32 v113, v88, v89
	global_store_dwordx4 v9, v[110:113], s[18:19]
	s_add_u32 s18, s18, s46
	s_addc_u32 s19, s19, 0
	ds_read_b32 v98, v2 offset:96
	ds_read_b32 v99, v2 offset:228
	ds_read_b32 v100, v2 offset:360
	ds_read_b32 v101, v2 offset:492
	ds_read_b32 v102, v2 offset:624
	ds_read_b32 v103, v2 offset:756
	ds_read_b32 v104, v2 offset:888
	ds_read_b32 v105, v2 offset:1020
	s_waitcnt lgkmcnt(8)
	v_cvt_pk_bf16_f32 v106, v90, v91
	v_cvt_pk_bf16_f32 v107, v92, v93
	v_cvt_pk_bf16_f32 v108, v94, v95
	v_cvt_pk_bf16_f32 v109, v96, v97
	global_store_dwordx4 v9, v[106:109], s[18:19]
	s_add_u32 s18, s18, s46
	s_addc_u32 s19, s19, 0
	s_waitcnt lgkmcnt(0)
	v_cvt_pk_bf16_f32 v110, v98, v99
	v_cvt_pk_bf16_f32 v111, v100, v101
	v_cvt_pk_bf16_f32 v112, v102, v103
	v_cvt_pk_bf16_f32 v113, v104, v105
	global_store_dwordx4 v9, v[110:113], s[18:19]
	s_cmp_eq_u32 s24, 0
	s_cbranch_scc1 .Ltra_done
	s_add_u32 s12, s12, 2048
	s_cmp_lt_u32 s12, 54272
	s_cselect_b32 s24, 1, 0
	s_cbranch_scc0 .Ltra_nonext17
	s_cmp_ge_u32 s12, 33280
	s_cselect_b32 s41, 1, 0
	s_cselect_b32 s26, 33280, 0
	s_sub_u32 s42, s12, s26
	s_cmp_ge_u32 s42, 12288
	s_cbranch_scc1 .Ltra_m20
	s_mul_i32 s43, s42, 43691
	s_lshr_b32 s43, s43, 24
	s_mul_i32 s26, s43, 384
	s_sub_u32 s44, s42, s26
	s_mov_b32 s14, s0
	s_mov_b32 s15, s1
	s_mov_b32 s36, 0xc000
	s_mov_b32 s37, 0x6000000
	s_mov_b32 s38, 0x0
	s_mov_b32 s39, 0x3000000
	s_mov_b32 s40, 0x1000
	s_branch .Ltra_dec_done19

.LBB0_1179:
	s_waitcnt vmcnt(0)
	s_barrier
	s_cmp_lt_u32 s96, 128
	s_cbranch_scc1 .LBB0_1180
	s_load_dwordx2 s[0:1], s[92:93], 0x58
	s_load_dwordx2 s[2:3], s[92:93], 0xb8
	s_load_dwordx2 s[4:5], s[92:93], 0xc0
	s_load_dwordx2 s[6:7], s[92:93], 0xc8
	s_load_dwordx2 s[8:9], s[92:93], 0xd0
	s_load_dwordx2 s[10:11], s[92:93], 0xe8
	v_and_b32_e32 v74, 63, v154
	v_lshrrev_b32_e32 v75, 6, v154
	v_mul_u32_u24_e32 v75, 0x2100, v75
	v_lshrrev_b32_e32 v3, 5, v74
	v_and_b32_e32 v4, 31, v74
	v_lshlrev_b32_e32 v4, 2, v4
	v_lshrrev_b32_e32 v5, 3, v74
	v_and_b32_e32 v6, 7, v74
	v_mul_u32_u24_e32 v2, 264, v6
	v_add_u32_e32 v2, v2, v5
	v_lshl_add_u32 v2, v2, 2, v75
	v_lshlrev_b32_e32 v6, 4, v6
	v_mul_u32_u24_e32 v1, 132, v5
	v_add3_u32 v1, v1, v6, v75
	v_readfirstlane_b32 s13, v154
	s_lshr_b32 s13, s13, 6
	s_lshl_b32 s26, s96, 3
	s_add_u32 s13, s13, s26
	s_sub_u32 s12, s13, 1024
	s_add_u32 s12, s12, 54272
	s_waitcnt lgkmcnt(0)
	s_cmp_ge_u32 s12, 66560
	s_cbranch_scc1 .Ltrs_done
	s_cmp_ge_u32 s12, 33280
	s_cselect_b32 s41, 1, 0
	s_cselect_b32 s26, 33280, 0
	s_sub_u32 s42, s12, s26
	s_cmp_ge_u32 s42, 12288
	s_cbranch_scc1 .Ltrs_m2
	s_mul_i32 s43, s42, 43691
	s_lshr_b32 s43, s43, 24
	s_mul_i32 s26, s43, 384
	s_sub_u32 s44, s42, s26
	s_mov_b32 s14, s0
	s_mov_b32 s15, s1
	s_mov_b32 s36, 0xc000
	s_mov_b32 s37, 0x6000000
	s_mov_b32 s38, 0x0
	s_mov_b32 s39, 0x3000000
	s_mov_b32 s40, 0x1000
	s_branch .Ltrs_dec_done1

.Ltrs_loop:
	s_add_u32 s12, s12, 1024
	s_cmp_lt_u32 s12, 66560
	s_cselect_b32 s24, 1, 0
	s_cbranch_scc0 .Ltrs_nonext8
	s_cmp_ge_u32 s12, 33280
	s_cselect_b32 s41, 1, 0
	s_cselect_b32 s26, 33280, 0
	s_sub_u32 s42, s12, s26
	s_cmp_ge_u32 s42, 12288
	s_cbranch_scc1 .Ltrs_m11
	s_mul_i32 s43, s42, 43691
	s_lshr_b32 s43, s43, 24
	s_mul_i32 s26, s43, 384
	s_sub_u32 s44, s42, s26
	s_mov_b32 s16, s0
	s_mov_b32 s17, s1
	s_mov_b32 s36, 0xc000
	s_mov_b32 s37, 0x6000000
	s_mov_b32 s38, 0x0
	s_mov_b32 s39, 0x3000000
	s_mov_b32 s40, 0x1000
	s_branch .Ltrs_dec_done10

.Ltrs_after9:
	ds_write_b32 v1, v10 offset:0
	ds_write_b32 v1, v11 offset:4
	ds_write_b32 v1, v12 offset:8
	ds_write_b32 v1, v13 offset:12
	ds_write_b32 v1, v14 offset:1056
	ds_write_b32 v1, v15 offset:1060
	ds_write_b32 v1, v16 offset:1064
	ds_write_b32 v1, v17 offset:1068
	ds_write_b32 v1, v18 offset:2112
	ds_write_b32 v1, v19 offset:2116
	ds_write_b32 v1, v20 offset:2120
	ds_write_b32 v1, v21 offset:2124
	ds_write_b32 v1, v22 offset:3168
	ds_write_b32 v1, v23 offset:3172
	ds_write_b32 v1, v24 offset:3176
	ds_write_b32 v1, v25 offset:3180
	ds_write_b32 v1, v26 offset:4224
	ds_write_b32 v1, v27 offset:4228
	ds_write_b32 v1, v28 offset:4232
	ds_write_b32 v1, v29 offset:4236
	ds_write_b32 v1, v30 offset:5280
	ds_write_b32 v1, v31 offset:5284
	ds_write_b32 v1, v32 offset:5288
	ds_write_b32 v1, v33 offset:5292
	ds_write_b32 v1, v34 offset:6336
	ds_write_b32 v1, v35 offset:6340
	ds_write_b32 v1, v36 offset:6344
	ds_write_b32 v1, v37 offset:6348
	ds_write_b32 v1, v38 offset:7392
	ds_write_b32 v1, v39 offset:7396
	ds_write_b32 v1, v40 offset:7400
	ds_write_b32 v1, v41 offset:7404
	v_mad_u32_u24 v9, v5, s22, v6
	s_lshl_b32 s46, s22, 3
	s_waitcnt lgkmcnt(0)
	ds_read_b32 v74, v2 offset:0
	ds_read_b32 v75, v2 offset:132
	ds_read_b32 v76, v2 offset:264
	ds_read_b32 v77, v2 offset:396
	ds_read_b32 v78, v2 offset:528
	ds_read_b32 v79, v2 offset:660
	ds_read_b32 v80, v2 offset:792
	ds_read_b32 v81, v2 offset:924
	ds_read_b32 v82, v2 offset:32
	ds_read_b32 v83, v2 offset:164
	ds_read_b32 v84, v2 offset:296
	ds_read_b32 v85, v2 offset:428
	ds_read_b32 v86, v2 offset:560
	ds_read_b32 v87, v2 offset:692
	ds_read_b32 v88, v2 offset:824
	ds_read_b32 v89, v2 offset:956
	s_waitcnt lgkmcnt(8)
	v_cvt_pk_bf16_f32 v106, v74, v75
	v_cvt_pk_bf16_f32 v107, v76, v77
	v_cvt_pk_bf16_f32 v108, v78, v79
	v_cvt_pk_bf16_f32 v109, v80, v81
	global_store_dwordx4 v9, v[106:109], s[18:19]
	s_add_u32 s18, s18, s46
	s_addc_u32 s19, s19, 0
	ds_read_b32 v90, v2 offset:64
	ds_read_b32 v91, v2 offset:196
	ds_read_b32 v92, v2 offset:328
	ds_read_b32 v93, v2 offset:460
	ds_read_b32 v94, v2 offset:592
	ds_read_b32 v95, v2 offset:724
	ds_read_b32 v96, v2 offset:856
	ds_read_b32 v97, v2 offset:988
	s_waitcnt lgkmcnt(8)
	v_cvt_pk_bf16_f32 v110, v82, v83
	v_cvt_pk_bf16_f32 v111, v84, v85
	v_cvt_pk_bf16_f32 v112, v86, v87
	v_cvt_pk_bf16_f32 v113, v88, v89
	global_store_dwordx4 v9, v[110:113], s[18:19]
	s_add_u32 s18, s18, s46
	s_addc_u32 s19, s19, 0
	ds_read_b32 v98, v2 offset:96
	ds_read_b32 v99, v2 offset:228
	ds_read_b32 v100, v2 offset:360
	ds_read_b32 v101, v2 offset:492
	ds_read_b32 v102, v2 offset:624
	ds_read_b32 v103, v2 offset:756
	ds_read_b32 v104, v2 offset:888
	ds_read_b32 v105, v2 offset:1020
	s_waitcnt lgkmcnt(8)
	v_cvt_pk_bf16_f32 v106, v90, v91
	v_cvt_pk_bf16_f32 v107, v92, v93
	v_cvt_pk_bf16_f32 v108, v94, v95
	v_cvt_pk_bf16_f32 v109, v96, v97
	global_store_dwordx4 v9, v[106:109], s[18:19]
	s_add_u32 s18, s18, s46
	s_addc_u32 s19, s19, 0
	s_waitcnt lgkmcnt(0)
	v_cvt_pk_bf16_f32 v110, v98, v99
	v_cvt_pk_bf16_f32 v111, v100, v101
	v_cvt_pk_bf16_f32 v112, v102, v103
	v_cvt_pk_bf16_f32 v113, v104, v105
	global_store_dwordx4 v9, v[110:113], s[18:19]
	s_cmp_eq_u32 s24, 0
	s_cbranch_scc1 .Ltrs_done
	s_add_u32 s12, s12, 1024
	s_cmp_lt_u32 s12, 66560
	s_cselect_b32 s24, 1, 0
	s_cbranch_scc0 .Ltrs_nonext17
	s_cmp_ge_u32 s12, 33280
	s_cselect_b32 s41, 1, 0
	s_cselect_b32 s26, 33280, 0
	s_sub_u32 s42, s12, s26
	s_cmp_ge_u32 s42, 12288
	s_cbranch_scc1 .Ltrs_m20
	s_mul_i32 s43, s42, 43691
	s_lshr_b32 s43, s43, 24
	s_mul_i32 s26, s43, 384
	s_sub_u32 s44, s42, s26
	s_mov_b32 s14, s0
	s_mov_b32 s15, s1
	s_mov_b32 s36, 0xc000
	s_mov_b32 s37, 0x6000000
	s_mov_b32 s38, 0x0
	s_mov_b32 s39, 0x3000000
	s_mov_b32 s40, 0x1000
	s_branch .Ltrs_dec_done19

.Ltrs_done:
	s_waitcnt vmcnt(0) lgkmcnt(0)
	s_branch .LBB0_1180
.LBB0_1180:
	v_writelane_b32 v232, s94, 6
	s_cmp_gt_i32 s87, 9
	s_nop 0
	v_writelane_b32 v232, s95, 7
	v_writelane_b32 v232, s87, 8
	s_cbranch_scc1 .LBB0_1326
	s_load_dword s0, s[92:93], 0x104
	s_waitcnt lgkmcnt(0)
	s_cmp_lt_i32 s0, 10
	s_cbranch_scc1 .LBB0_1326
	s_cmp_eq_u32 s87, 9
	s_cbranch_scc1 .LBB0_1250
	s_cmp_lt_u32 s0, 23
	s_mov_b64 s[0:1], -1
	s_cbranch_scc0 .LBB0_1237
	s_getreg_b32 s2, hwreg(HW_REG_XCC_ID, 0, 4)
	s_waitcnt vmcnt(0)
	s_waitcnt vmcnt(0)
	s_barrier
	s_mov_b64 s[0:1], exec
	v_readlane_b32 s4, v232, 4
	v_readlane_b32 s5, v232, 5
	s_and_b64 s[4:5], s[0:1], s[4:5]
	s_mov_b64 exec, s[4:5]
	s_cbranch_execz .LBB0_1236
	s_add_i32 s3, 0, 0x20000
	v_mov_b32_e32 v1, s3
	s_waitcnt vmcnt(0) expcnt(0) lgkmcnt(0)
	ds_read_b32 v3, v1
	s_add_i32 s3, 0, 0x20004
	v_mov_b32_e32 v1, s3
	ds_read_b32 v1, v1
	s_and_b32 s33, s2, 15
	s_waitcnt lgkmcnt(1)
	v_cmp_ne_u32_e32 vcc, 0, v3
	s_cbranch_vccnz .LBB0_1200
	s_add_u32 s2, s90, 0x2c918200
	s_addc_u32 s3, s91, 0
	s_add_u32 s4, s90, 0x2c918400
	s_addc_u32 s5, s91, 0
	s_add_u32 s6, s90, 0x2c918500
	s_addc_u32 s7, s91, 0
	s_add_u32 s8, s90, 0x2c918600
	s_addc_u32 s9, s91, 0
	s_add_u32 s10, s90, 0x2c918700
	s_addc_u32 s11, s91, 0
	s_add_u32 s12, s90, 0x2c918800
	s_addc_u32 s13, s91, 0
	s_add_u32 s14, s90, 0x2c918900
	s_addc_u32 s15, s91, 0
	s_add_u32 s16, s90, 0x2c918a00
	s_addc_u32 s17, s91, 0
	s_add_u32 s18, s90, 0x2c918b00
	s_addc_u32 s19, s91, 0
	s_add_u32 s20, s90, 0x2c918c00
	s_addc_u32 s21, s91, 0
	s_add_u32 s22, s90, 0x2c918d00
	s_addc_u32 s23, s91, 0
	s_add_u32 s24, s90, 0x2c918e00
	s_addc_u32 s25, s91, 0
	s_add_u32 s26, s90, 0x2c918f00
	s_addc_u32 s27, s91, 0
	s_add_u32 s28, s90, 0x2c919000
	s_addc_u32 s29, s91, 0
	s_add_u32 s30, s90, 0x2c919100
	s_addc_u32 s31, s91, 0
	s_add_u32 s34, s90, 0x2c919200
	s_addc_u32 s35, s91, 0
	s_mul_i32 s44, s95, s97
	s_add_u32 s36, s90, 0x2c919300
	s_mul_i32 s44, s44, s94
	s_addc_u32 s37, s91, 0
	s_mov_b32 s45, 1
	v_mov_b32_e32 v17, 0
	s_branch .LBB0_1188
